# adaLN partial loop (P0) software-pipelined: two banks, 8 w_ada loads in flight per wave; plus SwiGLU epilogue packed
# speedup vs baseline: 1.0021x; 1.0021x over previous
; #define LDS_WAIT() asm volatile("s_waitcnt lgkmcnt(0)" ::: "memory")
; __device__ __forceinline__ float silu_f(float x) { return x / (1.0f + __expf(-x)); }
; __device__ __forceinline__ void p_adaln_partial(const Frame& F, const float* __restrict__ c, const float* __restrict__ cctx, const float* __restrict__ w_ada, float* modp) {
;     ...
;     for (int it = gw; it < 2 * 72 * 16; it += NGW) {
;         const int ks = it & 15, cb = (it >> 4) % 72, l = it / (72 * 16), k0 = ks * 128;
;         for (int i = 0; i < 34; ++i) { const int idx = F.lane + 64 * i, r = idx >> 7, kk = idx & 127;
;             const float x = (r < 16) ? c[r * DM + k0 + kk] : cctx[k0 + kk]; ca[kk * 20 + r] = silu_f(x); }
;         LDS_WAIT();
;         f32x4 acc[17];
; #pragma unroll
;         for (int r = 0; r < 17; ++r) acc[r] = (f32x4){0.f, 0.f, 0.f, 0.f};
;         const float* wp = w_ada + ((size_t)l * DM + k0) * NMODC + cb * 256 + F.lane * 4;
; #pragma unroll 4
;         for (int kk = 0; kk < 128; ++kk) {
;             const f32x4 w = *(const f32x4*)(wp + (size_t)kk * NMODC);
.LBB0_16:
	s_cmp_lt_u32 s7, 32
	s_cselect_b64 s[4:5], -1, 0
	s_and_b64 s[4:5], s[4:5], exec
	s_cselect_b32 s36, s6, 0
	s_cselect_b32 s5, s3, s9
	s_cselect_b32 s4, s2, s8
	v_or_b32_e32 v72, s36, v2
	v_lshl_add_u64 v[4:5], v[72:73], 2, s[4:5]
	v_add_u32_e32 v72, s36, v2
	global_load_dword v6, v[4:5], off
	v_lshl_add_u64 v[4:5], v[72:73], 2, s[4:5]
	global_load_dword v4, v[4:5], off offset:256
	s_add_i32 s7, s7, 2
	s_addk_i32 s6, 0x800
	s_cmpk_eq_u32 s6, 0x8800
	s_waitcnt vmcnt(1)
	v_mul_f32_e32 v5, 0xbfb8aa3b, v6
	v_exp_f32_e32 v5, v5
	s_waitcnt vmcnt(0)
	v_mul_f32_e32 v7, 0xbfb8aa3b, v4
	v_exp_f32_e32 v7, v7
	v_add_f32_e32 v5, 1.0, v5
	v_div_scale_f32 v8, s[4:5], v5, v5, v6
	v_add_f32_e32 v7, 1.0, v7
	v_rcp_f32_e32 v10, v8
	v_div_scale_f32 v11, s[4:5], v7, v7, v4
	v_rcp_f32_e32 v13, v11
	v_fma_f32 v14, -v8, v10, 1.0
	v_div_scale_f32 v9, vcc, v6, v5, v6
	v_fmac_f32_e32 v10, v14, v10
	v_fma_f32 v14, -v11, v13, 1.0
	v_div_scale_f32 v12, s[4:5], v4, v7, v4
	v_mul_f32_e32 v15, v9, v10
	v_fmac_f32_e32 v13, v14, v13
	v_fma_f32 v14, -v8, v15, v9
	v_mul_f32_e32 v16, v12, v13
	v_fmac_f32_e32 v15, v14, v10
	v_fma_f32 v14, -v11, v16, v12
	v_fma_f32 v8, -v8, v15, v9
	v_fmac_f32_e32 v16, v14, v13
	v_div_fmas_f32 v8, v8, v10, v15
	v_fma_f32 v9, -v11, v16, v12
	s_mov_b64 vcc, s[4:5]
	v_div_fixup_f32 v5, v8, v5, v6
	v_div_fmas_f32 v6, v9, v13, v16
	v_div_fixup_f32 v4, v6, v7, v4
	ds_write2st64_b32 v3, v5, v4 offset1:20
	v_add_u32_e32 v3, 4, v3
	s_cbranch_scc0 .LBB0_16
	s_and_b32 s4, s10, 15
	s_mul_i32 s6, s4, 0x900000
	s_ashr_i32 s4, s34, 4
	s_mul_hi_i32 s5, s4, 0x38e38e39
	s_lshr_b32 s7, s5, 31
	s_lshr_b32 s5, s5, 4
	s_add_i32 s5, s5, s7
	s_mulk_i32 s5, 0x48
	s_sub_i32 s4, s4, s5
	s_mul_hi_i32 s5, s34, 0x38e38e39
	s_lshr_b32 s7, s5, 31
	s_ashr_i32 s36, s5, 8
	s_add_i32 s36, s36, s7
	s_lshl_b32 s4, s4, 8
	s_ashr_i32 s5, s4, 31
	s_mul_i32 s37, s36, 0x9000000
	s_mul_hi_i32 s7, s36, 0x9000000
	s_add_u32 s6, s37, s6
	s_addc_u32 s7, s7, 0
	s_lshl_b64 s[4:5], s[4:5], 2
	s_waitcnt lgkmcnt(0)
	s_add_u32 s38, s6, s4
	s_addc_u32 s39, s7, s5
	v_mov_b32_e32 v2, 0
	s_mov_b64 s[6:7], 0
	s_mov_b32 s37, s19
	v_mov_b32_e32 v3, v2
	v_mov_b32_e32 v4, v2
	v_mov_b32_e32 v5, v2
	v_mov_b32_e32 v6, v2
	v_mov_b32_e32 v7, v2
	v_mov_b32_e32 v8, v2
	v_mov_b32_e32 v9, v2
	v_mov_b32_e32 v10, v2
	v_mov_b32_e32 v11, v2
	v_mov_b32_e32 v12, v2
	v_mov_b32_e32 v13, v2
	v_mov_b32_e32 v14, v2
	v_mov_b32_e32 v15, v2
	v_mov_b32_e32 v16, v2
	v_mov_b32_e32 v17, v2
	v_mov_b32_e32 v18, v2
	v_mov_b32_e32 v19, v2
	v_mov_b32_e32 v20, v2
	v_mov_b32_e32 v21, v2
	v_mov_b32_e32 v22, v2
	v_mov_b32_e32 v23, v2
	v_mov_b32_e32 v24, v2
	v_mov_b32_e32 v25, v2
	v_mov_b32_e32 v26, v2
	v_mov_b32_e32 v27, v2
	v_mov_b32_e32 v28, v2
	v_mov_b32_e32 v29, v2
	v_mov_b32_e32 v30, v2
	v_mov_b32_e32 v31, v2
	v_mov_b32_e32 v32, v2
	v_mov_b32_e32 v33, v2
	v_mov_b32_e32 v34, v2
	v_mov_b32_e32 v35, v2
	v_mov_b32_e32 v36, v2
	v_mov_b32_e32 v37, v2
	v_mov_b32_e32 v38, v2
	v_mov_b32_e32 v39, v2
	v_mov_b32_e32 v40, v2
	v_mov_b32_e32 v41, v2
	v_mov_b32_e32 v42, v2
	v_mov_b32_e32 v43, v2
	v_mov_b32_e32 v44, v2
	v_mov_b32_e32 v45, v2
	v_mov_b32_e32 v46, v2
	v_mov_b32_e32 v47, v2
	v_mov_b32_e32 v48, v2
	v_mov_b32_e32 v49, v2
	v_mov_b32_e32 v50, v2
	v_mov_b32_e32 v51, v2
	v_mov_b32_e32 v52, v2
	v_mov_b32_e32 v53, v2
	v_mov_b32_e32 v54, v2
	v_mov_b32_e32 v55, v2
	v_mov_b32_e32 v56, v2
	v_mov_b32_e32 v57, v2
	v_mov_b32_e32 v58, v2
	v_mov_b32_e32 v59, v2
	v_mov_b32_e32 v60, v2
	v_mov_b32_e32 v61, v2
	v_mov_b32_e32 v62, v2
	v_mov_b32_e32 v63, v2
	v_mov_b32_e32 v64, v2
	v_mov_b32_e32 v65, v2
	v_mov_b32_e32 v66, v2
	v_mov_b32_e32 v67, v2
	v_mov_b32_e32 v68, v2
	v_mov_b32_e32 v69, v2
	v_lshl_add_u64 v[78:79], v[74:75], 0, s[38:39]
	s_mov_b64 s[100:101], s[6:7]
	v_lshl_add_u64 v[80:81], v[78:79], 0, s[100:101]
	v_add_co_u32_e32 v150, vcc, s11, v80
	global_load_dwordx4 v[82:85], v[80:81], off
	s_nop 0
	v_addc_co_u32_e32 v151, vcc, 0, v81, vcc
	v_add_co_u32_e32 v154, vcc, s20, v80
	s_nop 1
	v_addc_co_u32_e32 v155, vcc, 0, v81, vcc
	v_add_co_u32_e32 v158, vcc, s21, v80
	s_nop 1
	v_addc_co_u32_e32 v159, vcc, 0, v81, vcc
	global_load_dwordx4 v[150:153], v[150:151], off
	global_load_dwordx4 v[154:157], v[154:155], off
	global_load_dwordx4 v[158:161], v[158:159], off
; #define LAS __attribute__((address_space(3)))
; __device__ __forceinline__ void p_adaln_partial(const Frame& F, const float* __restrict__ c, const float* __restrict__ cctx, const float* __restrict__ w_ada, float* modp) {
;     ...
;         for (int kk = 0; kk < 128; ++kk) {
;             const f32x4 w = *(const f32x4*)(wp + (size_t)kk * NMODC);
;             const LAS f32x4* cp = (const LAS f32x4*)(ca + kk * 20); const f32x4 c0 = cp[0], c1 = cp[1], c2 = cp[2], c3 = cp[3]; const float c16 = ca[kk * 20 + 16];
; #pragma unroll
;             for (int j = 0; j < 4; ++j) { acc[j] += c0[j] * w; acc[4 + j] += c1[j] * w; acc[8 + j] += c2[j] * w; acc[12 + j] += c3[j] * w; }
;             acc[16] += c16 * w; }
.LBB0_18:
	s_add_u32 s100, s6, 0x48000
	s_addc_u32 s101, s7, 0
	s_cmp_eq_u32 s100, 0x900000
	s_cselect_b32 s100, 0, s100
	v_lshl_add_u64 v[214:215], v[78:79], 0, s[100:101]
	v_add_co_u32_e32 v202, vcc, s11, v214
	global_load_dwordx4 v[198:201], v[214:215], off
	s_nop 0
	v_addc_co_u32_e32 v203, vcc, 0, v215, vcc
	v_add_co_u32_e32 v206, vcc, s20, v214
	s_nop 1
	v_addc_co_u32_e32 v207, vcc, 0, v215, vcc
	v_add_co_u32_e32 v210, vcc, s21, v214
	s_nop 1
	v_addc_co_u32_e32 v211, vcc, 0, v215, vcc
	global_load_dwordx4 v[202:205], v[202:203], off
	global_load_dwordx4 v[206:209], v[206:207], off
	global_load_dwordx4 v[210:213], v[210:211], off
	v_mov_b32_e32 v72, s37
	ds_read_b128 v[86:89], v72
	ds_read_b128 v[90:93], v72 offset:16
	ds_read_b128 v[94:97], v72 offset:32
	ds_read_b128 v[98:101], v72 offset:48
	ds_read2_b32 v[162:163], v72 offset0:16 offset1:36
	ds_read_b128 v[102:105], v72 offset:80
	ds_read_b128 v[106:109], v72 offset:96
	ds_read_b128 v[110:113], v72 offset:112
	ds_read_b128 v[114:117], v72 offset:128
	ds_read_b128 v[118:121], v72 offset:160
	ds_read_b128 v[122:125], v72 offset:176
	ds_read_b128 v[126:129], v72 offset:192
	ds_read_b128 v[130:133], v72 offset:208
	ds_read2_b32 v[164:165], v72 offset0:56 offset1:76
	ds_read_b128 v[134:137], v72 offset:240
	ds_read_b128 v[138:141], v72 offset:256
	ds_read_b128 v[142:145], v72 offset:272
	ds_read_b128 v[146:149], v72 offset:288
	s_waitcnt lgkmcnt(14)
	v_mov_b32_e32 v72, v89
	v_mov_b32_e32 v80, v93
	v_mov_b32_e32 v166, v97
	v_mov_b32_e32 v168, v101
	s_waitcnt lgkmcnt(12)
	v_mov_b32_e32 v170, v105
	s_waitcnt lgkmcnt(11)
	v_mov_b32_e32 v172, v109
	s_waitcnt lgkmcnt(10)
	v_mov_b32_e32 v174, v113
	s_waitcnt lgkmcnt(9)
	v_mov_b32_e32 v176, v117
	v_mov_b32_e32 v178, v163
	s_add_u32 s6, s6, 0x48000
	s_waitcnt lgkmcnt(8)
	v_mov_b32_e32 v180, v121
	s_waitcnt lgkmcnt(7)
	v_mov_b32_e32 v182, v125
	s_waitcnt lgkmcnt(6)
	v_mov_b32_e32 v184, v129
	s_waitcnt lgkmcnt(5)
	v_mov_b32_e32 v186, v133
	s_addc_u32 s7, s7, 0
	s_addk_i32 s37, 0x140
	s_waitcnt lgkmcnt(3)
	v_mov_b32_e32 v188, v137
	s_waitcnt lgkmcnt(2)
	v_mov_b32_e32 v190, v141
	s_waitcnt lgkmcnt(1)
	v_mov_b32_e32 v192, v145
	s_waitcnt lgkmcnt(0)
	v_mov_b32_e32 v194, v149
	v_mov_b32_e32 v196, v165
	s_cmp_eq_u32 s6, 0x900000
	s_waitcnt vmcnt(7)
	v_pk_fma_f32 v[68:69], v[84:85], v[86:87], v[68:69] op_sel_hi:[1,0,1]
	v_pk_fma_f32 v[66:67], v[82:83], v[86:87], v[66:67] op_sel_hi:[1,0,1]
	v_pk_fma_f32 v[64:65], v[84:85], v[86:87], v[64:65] op_sel:[0,1,0]
	v_pk_fma_f32 v[62:63], v[82:83], v[86:87], v[62:63] op_sel:[0,1,0]
	v_pk_fma_f32 v[58:59], v[82:83], v[88:89], v[58:59] op_sel_hi:[1,0,1]
	v_pk_fma_f32 v[60:61], v[84:85], v[88:89], v[60:61] op_sel_hi:[1,0,1]
	v_pk_fma_f32 v[54:55], v[82:83], v[72:73], v[54:55] op_sel_hi:[1,0,1]
	v_pk_fma_f32 v[56:57], v[84:85], v[72:73], v[56:57] op_sel_hi:[1,0,1]
	v_pk_fma_f32 v[52:53], v[84:85], v[90:91], v[52:53] op_sel_hi:[1,0,1]
	v_pk_fma_f32 v[50:51], v[82:83], v[90:91], v[50:51] op_sel_hi:[1,0,1]
	v_pk_fma_f32 v[48:49], v[84:85], v[90:91], v[48:49] op_sel:[0,1,0]
	v_pk_fma_f32 v[46:47], v[82:83], v[90:91], v[46:47] op_sel:[0,1,0]
	v_pk_fma_f32 v[42:43], v[82:83], v[92:93], v[42:43] op_sel_hi:[1,0,1]
	v_pk_fma_f32 v[44:45], v[84:85], v[92:93], v[44:45] op_sel_hi:[1,0,1]
	v_pk_fma_f32 v[38:39], v[82:83], v[80:81], v[38:39] op_sel_hi:[1,0,1]
	v_pk_fma_f32 v[40:41], v[84:85], v[80:81], v[40:41] op_sel_hi:[1,0,1]
	v_pk_fma_f32 v[36:37], v[84:85], v[94:95], v[36:37] op_sel_hi:[1,0,1]
	v_pk_fma_f32 v[34:35], v[82:83], v[94:95], v[34:35] op_sel_hi:[1,0,1]
	v_pk_fma_f32 v[32:33], v[84:85], v[94:95], v[32:33] op_sel:[0,1,0]
	v_pk_fma_f32 v[30:31], v[82:83], v[94:95], v[30:31] op_sel:[0,1,0]
	v_pk_fma_f32 v[26:27], v[82:83], v[96:97], v[26:27] op_sel_hi:[1,0,1]
	v_pk_fma_f32 v[28:29], v[84:85], v[96:97], v[28:29] op_sel_hi:[1,0,1]
	v_pk_fma_f32 v[22:23], v[82:83], v[166:167], v[22:23] op_sel_hi:[1,0,1]
	v_pk_fma_f32 v[24:25], v[84:85], v[166:167], v[24:25] op_sel_hi:[1,0,1]
	v_pk_fma_f32 v[20:21], v[84:85], v[98:99], v[20:21] op_sel_hi:[1,0,1]
	v_pk_fma_f32 v[18:19], v[82:83], v[98:99], v[18:19] op_sel_hi:[1,0,1]
	v_pk_fma_f32 v[16:17], v[84:85], v[98:99], v[16:17] op_sel:[0,1,0]
	v_pk_fma_f32 v[14:15], v[82:83], v[98:99], v[14:15] op_sel:[0,1,0]
	v_pk_fma_f32 v[10:11], v[82:83], v[100:101], v[10:11] op_sel_hi:[1,0,1]
	v_pk_fma_f32 v[12:13], v[84:85], v[100:101], v[12:13] op_sel_hi:[1,0,1]
	v_pk_fma_f32 v[6:7], v[82:83], v[168:169], v[6:7] op_sel_hi:[1,0,1]
	v_pk_fma_f32 v[8:9], v[84:85], v[168:169], v[8:9] op_sel_hi:[1,0,1]
	v_pk_fma_f32 v[2:3], v[82:83], v[162:163], v[2:3] op_sel_hi:[1,0,1]
	v_pk_fma_f32 v[4:5], v[84:85], v[162:163], v[4:5] op_sel_hi:[1,0,1]
	s_waitcnt vmcnt(6)
; #define LAS __attribute__((address_space(3)))
; __device__ __forceinline__ void p_adaln_partial(const Frame& F, const float* __restrict__ c, const float* __restrict__ cctx, const float* __restrict__ w_ada, float* modp) {
;     ...
;         for (int kk = 0; kk < 128; ++kk) {
;             const f32x4 w = *(const f32x4*)(wp + (size_t)kk * NMODC);
;             const LAS f32x4* cp = (const LAS f32x4*)(ca + kk * 20); const f32x4 c0 = cp[0], c1 = cp[1], c2 = cp[2], c3 = cp[3]; const float c16 = ca[kk * 20 + 16];
; #pragma unroll
;             for (int j = 0; j < 4; ++j) { acc[j] += c0[j] * w; acc[4 + j] += c1[j] * w; acc[8 + j] += c2[j] * w; acc[12 + j] += c3[j] * w; }
;             acc[16] += c16 * w; }
	v_pk_fma_f32 v[66:67], v[150:151], v[102:103], v[66:67] op_sel_hi:[1,0,1]
	v_pk_fma_f32 v[68:69], v[152:153], v[102:103], v[68:69] op_sel_hi:[1,0,1]
	v_pk_fma_f32 v[62:63], v[150:151], v[102:103], v[62:63] op_sel:[0,1,0]
	v_pk_fma_f32 v[64:65], v[152:153], v[102:103], v[64:65] op_sel:[0,1,0]
	v_pk_fma_f32 v[58:59], v[150:151], v[104:105], v[58:59] op_sel_hi:[1,0,1]
	v_pk_fma_f32 v[60:61], v[152:153], v[104:105], v[60:61] op_sel_hi:[1,0,1]
	v_pk_fma_f32 v[50:51], v[150:151], v[106:107], v[50:51] op_sel_hi:[1,0,1]
	v_pk_fma_f32 v[52:53], v[152:153], v[106:107], v[52:53] op_sel_hi:[1,0,1]
	v_pk_fma_f32 v[46:47], v[150:151], v[106:107], v[46:47] op_sel:[0,1,0]
	v_pk_fma_f32 v[48:49], v[152:153], v[106:107], v[48:49] op_sel:[0,1,0]
	v_pk_fma_f32 v[42:43], v[150:151], v[108:109], v[42:43] op_sel_hi:[1,0,1]
	v_pk_fma_f32 v[44:45], v[152:153], v[108:109], v[44:45] op_sel_hi:[1,0,1]
	v_pk_fma_f32 v[34:35], v[150:151], v[110:111], v[34:35] op_sel_hi:[1,0,1]
	v_pk_fma_f32 v[36:37], v[152:153], v[110:111], v[36:37] op_sel_hi:[1,0,1]
	v_pk_fma_f32 v[30:31], v[150:151], v[110:111], v[30:31] op_sel:[0,1,0]
	v_pk_fma_f32 v[32:33], v[152:153], v[110:111], v[32:33] op_sel:[0,1,0]
	v_pk_fma_f32 v[26:27], v[150:151], v[112:113], v[26:27] op_sel_hi:[1,0,1]
	v_pk_fma_f32 v[28:29], v[152:153], v[112:113], v[28:29] op_sel_hi:[1,0,1]
	v_pk_fma_f32 v[18:19], v[150:151], v[114:115], v[18:19] op_sel_hi:[1,0,1]
	v_pk_fma_f32 v[20:21], v[152:153], v[114:115], v[20:21] op_sel_hi:[1,0,1]
	v_pk_fma_f32 v[14:15], v[150:151], v[114:115], v[14:15] op_sel:[0,1,0]
	v_pk_fma_f32 v[16:17], v[152:153], v[114:115], v[16:17] op_sel:[0,1,0]
	v_pk_fma_f32 v[10:11], v[150:151], v[116:117], v[10:11] op_sel_hi:[1,0,1]
	v_pk_fma_f32 v[12:13], v[152:153], v[116:117], v[12:13] op_sel_hi:[1,0,1]
	v_pk_fma_f32 v[54:55], v[150:151], v[170:171], v[54:55] op_sel_hi:[1,0,1]
	v_pk_fma_f32 v[56:57], v[152:153], v[170:171], v[56:57] op_sel_hi:[1,0,1]
	v_pk_fma_f32 v[38:39], v[150:151], v[172:173], v[38:39] op_sel_hi:[1,0,1]
	v_pk_fma_f32 v[40:41], v[152:153], v[172:173], v[40:41] op_sel_hi:[1,0,1]
	v_pk_fma_f32 v[22:23], v[150:151], v[174:175], v[22:23] op_sel_hi:[1,0,1]
	v_pk_fma_f32 v[24:25], v[152:153], v[174:175], v[24:25] op_sel_hi:[1,0,1]
	v_pk_fma_f32 v[6:7], v[150:151], v[176:177], v[6:7] op_sel_hi:[1,0,1]
	v_pk_fma_f32 v[8:9], v[152:153], v[176:177], v[8:9] op_sel_hi:[1,0,1]
	v_pk_fma_f32 v[2:3], v[150:151], v[178:179], v[2:3] op_sel_hi:[1,0,1]
	v_pk_fma_f32 v[4:5], v[152:153], v[178:179], v[4:5] op_sel_hi:[1,0,1]
	s_waitcnt vmcnt(5)
	v_pk_fma_f32 v[68:69], v[156:157], v[118:119], v[68:69] op_sel_hi:[1,0,1]
	v_pk_fma_f32 v[66:67], v[154:155], v[118:119], v[66:67] op_sel_hi:[1,0,1]
	v_pk_fma_f32 v[64:65], v[156:157], v[118:119], v[64:65] op_sel:[0,1,0]
	v_pk_fma_f32 v[62:63], v[154:155], v[118:119], v[62:63] op_sel:[0,1,0]
	v_pk_fma_f32 v[60:61], v[156:157], v[120:121], v[60:61] op_sel_hi:[1,0,1]
	v_pk_fma_f32 v[58:59], v[154:155], v[120:121], v[58:59] op_sel_hi:[1,0,1]
	v_pk_fma_f32 v[52:53], v[156:157], v[122:123], v[52:53] op_sel_hi:[1,0,1]
	v_pk_fma_f32 v[50:51], v[154:155], v[122:123], v[50:51] op_sel_hi:[1,0,1]
	v_pk_fma_f32 v[48:49], v[156:157], v[122:123], v[48:49] op_sel:[0,1,0]
	v_pk_fma_f32 v[46:47], v[154:155], v[122:123], v[46:47] op_sel:[0,1,0]
	v_pk_fma_f32 v[44:45], v[156:157], v[124:125], v[44:45] op_sel_hi:[1,0,1]
	v_pk_fma_f32 v[42:43], v[154:155], v[124:125], v[42:43] op_sel_hi:[1,0,1]
	v_pk_fma_f32 v[36:37], v[156:157], v[126:127], v[36:37] op_sel_hi:[1,0,1]
	v_pk_fma_f32 v[34:35], v[154:155], v[126:127], v[34:35] op_sel_hi:[1,0,1]
	v_pk_fma_f32 v[32:33], v[156:157], v[126:127], v[32:33] op_sel:[0,1,0]
	v_pk_fma_f32 v[30:31], v[154:155], v[126:127], v[30:31] op_sel:[0,1,0]
	v_pk_fma_f32 v[28:29], v[156:157], v[128:129], v[28:29] op_sel_hi:[1,0,1]
	v_pk_fma_f32 v[26:27], v[154:155], v[128:129], v[26:27] op_sel_hi:[1,0,1]
	v_pk_fma_f32 v[20:21], v[156:157], v[130:131], v[20:21] op_sel_hi:[1,0,1]
	v_pk_fma_f32 v[18:19], v[154:155], v[130:131], v[18:19] op_sel_hi:[1,0,1]
	v_pk_fma_f32 v[16:17], v[156:157], v[130:131], v[16:17] op_sel:[0,1,0]
	v_pk_fma_f32 v[14:15], v[154:155], v[130:131], v[14:15] op_sel:[0,1,0]
	v_pk_fma_f32 v[12:13], v[156:157], v[132:133], v[12:13] op_sel_hi:[1,0,1]
	v_pk_fma_f32 v[10:11], v[154:155], v[132:133], v[10:11] op_sel_hi:[1,0,1]
	v_pk_fma_f32 v[56:57], v[156:157], v[180:181], v[56:57] op_sel_hi:[1,0,1]
	v_pk_fma_f32 v[54:55], v[154:155], v[180:181], v[54:55] op_sel_hi:[1,0,1]
	v_pk_fma_f32 v[40:41], v[156:157], v[182:183], v[40:41] op_sel_hi:[1,0,1]
	v_pk_fma_f32 v[38:39], v[154:155], v[182:183], v[38:39] op_sel_hi:[1,0,1]
	v_pk_fma_f32 v[24:25], v[156:157], v[184:185], v[24:25] op_sel_hi:[1,0,1]
	v_pk_fma_f32 v[22:23], v[154:155], v[184:185], v[22:23] op_sel_hi:[1,0,1]
	v_pk_fma_f32 v[8:9], v[156:157], v[186:187], v[8:9] op_sel_hi:[1,0,1]
	v_pk_fma_f32 v[6:7], v[154:155], v[186:187], v[6:7] op_sel_hi:[1,0,1]
	v_pk_fma_f32 v[4:5], v[156:157], v[164:165], v[4:5] op_sel_hi:[1,0,1]
	v_pk_fma_f32 v[2:3], v[154:155], v[164:165], v[2:3] op_sel_hi:[1,0,1]
	s_waitcnt vmcnt(4)
; #define LAS __attribute__((address_space(3)))
; __device__ __forceinline__ void p_adaln_partial(const Frame& F, const float* __restrict__ c, const float* __restrict__ cctx, const float* __restrict__ w_ada, float* modp) {
;     ...
;         for (int kk = 0; kk < 128; ++kk) {
;             const f32x4 w = *(const f32x4*)(wp + (size_t)kk * NMODC);
;             const LAS f32x4* cp = (const LAS f32x4*)(ca + kk * 20); const f32x4 c0 = cp[0], c1 = cp[1], c2 = cp[2], c3 = cp[3]; const float c16 = ca[kk * 20 + 16];
; #pragma unroll
;             for (int j = 0; j < 4; ++j) { acc[j] += c0[j] * w; acc[4 + j] += c1[j] * w; acc[8 + j] += c2[j] * w; acc[12 + j] += c3[j] * w; }
;             acc[16] += c16 * w; }
	v_pk_fma_f32 v[68:69], v[160:161], v[134:135], v[68:69] op_sel_hi:[1,0,1]
	v_pk_fma_f32 v[66:67], v[158:159], v[134:135], v[66:67] op_sel_hi:[1,0,1]
	v_pk_fma_f32 v[64:65], v[160:161], v[134:135], v[64:65] op_sel:[0,1,0]
	v_pk_fma_f32 v[62:63], v[158:159], v[134:135], v[62:63] op_sel:[0,1,0]
	v_pk_fma_f32 v[60:61], v[160:161], v[136:137], v[60:61] op_sel_hi:[1,0,1]
	v_pk_fma_f32 v[58:59], v[158:159], v[136:137], v[58:59] op_sel_hi:[1,0,1]
	v_pk_fma_f32 v[56:57], v[160:161], v[188:189], v[56:57] op_sel_hi:[1,0,1]
	v_pk_fma_f32 v[54:55], v[158:159], v[188:189], v[54:55] op_sel_hi:[1,0,1]
	v_pk_fma_f32 v[52:53], v[160:161], v[138:139], v[52:53] op_sel_hi:[1,0,1]
	v_pk_fma_f32 v[50:51], v[158:159], v[138:139], v[50:51] op_sel_hi:[1,0,1]
	v_pk_fma_f32 v[48:49], v[160:161], v[138:139], v[48:49] op_sel:[0,1,0]
	v_pk_fma_f32 v[46:47], v[158:159], v[138:139], v[46:47] op_sel:[0,1,0]
	v_pk_fma_f32 v[44:45], v[160:161], v[140:141], v[44:45] op_sel_hi:[1,0,1]
	v_pk_fma_f32 v[42:43], v[158:159], v[140:141], v[42:43] op_sel_hi:[1,0,1]
	v_pk_fma_f32 v[40:41], v[160:161], v[190:191], v[40:41] op_sel_hi:[1,0,1]
	v_pk_fma_f32 v[38:39], v[158:159], v[190:191], v[38:39] op_sel_hi:[1,0,1]
	v_pk_fma_f32 v[36:37], v[160:161], v[142:143], v[36:37] op_sel_hi:[1,0,1]
	v_pk_fma_f32 v[34:35], v[158:159], v[142:143], v[34:35] op_sel_hi:[1,0,1]
	v_pk_fma_f32 v[32:33], v[160:161], v[142:143], v[32:33] op_sel:[0,1,0]
	v_pk_fma_f32 v[30:31], v[158:159], v[142:143], v[30:31] op_sel:[0,1,0]
	v_pk_fma_f32 v[28:29], v[160:161], v[144:145], v[28:29] op_sel_hi:[1,0,1]
	v_pk_fma_f32 v[26:27], v[158:159], v[144:145], v[26:27] op_sel_hi:[1,0,1]
	v_pk_fma_f32 v[24:25], v[160:161], v[192:193], v[24:25] op_sel_hi:[1,0,1]
	v_pk_fma_f32 v[22:23], v[158:159], v[192:193], v[22:23] op_sel_hi:[1,0,1]
	v_pk_fma_f32 v[20:21], v[160:161], v[146:147], v[20:21] op_sel_hi:[1,0,1]
	v_pk_fma_f32 v[18:19], v[158:159], v[146:147], v[18:19] op_sel_hi:[1,0,1]
	v_pk_fma_f32 v[16:17], v[160:161], v[146:147], v[16:17] op_sel:[0,1,0]
	v_pk_fma_f32 v[14:15], v[158:159], v[146:147], v[14:15] op_sel:[0,1,0]
	v_pk_fma_f32 v[12:13], v[160:161], v[148:149], v[12:13] op_sel_hi:[1,0,1]
	v_pk_fma_f32 v[10:11], v[158:159], v[148:149], v[10:11] op_sel_hi:[1,0,1]
	v_pk_fma_f32 v[8:9], v[160:161], v[194:195], v[8:9] op_sel_hi:[1,0,1]
	v_pk_fma_f32 v[6:7], v[158:159], v[194:195], v[6:7] op_sel_hi:[1,0,1]
	v_pk_fma_f32 v[4:5], v[160:161], v[196:197], v[4:5] op_sel_hi:[1,0,1]
	v_pk_fma_f32 v[2:3], v[158:159], v[196:197], v[2:3] op_sel_hi:[1,0,1]
	s_add_u32 s100, s6, 0x48000
	s_addc_u32 s101, s7, 0
	s_cmp_eq_u32 s100, 0x900000
	s_cselect_b32 s100, 0, s100
	v_lshl_add_u64 v[80:81], v[78:79], 0, s[100:101]
	v_add_co_u32_e32 v150, vcc, s11, v80
	global_load_dwordx4 v[82:85], v[80:81], off
	s_nop 0
	v_addc_co_u32_e32 v151, vcc, 0, v81, vcc
	v_add_co_u32_e32 v154, vcc, s20, v80
	s_nop 1
	v_addc_co_u32_e32 v155, vcc, 0, v81, vcc
	v_add_co_u32_e32 v158, vcc, s21, v80
	s_nop 1
	v_addc_co_u32_e32 v159, vcc, 0, v81, vcc
	global_load_dwordx4 v[150:153], v[150:151], off
	global_load_dwordx4 v[154:157], v[154:155], off
	global_load_dwordx4 v[158:161], v[158:159], off
	v_mov_b32_e32 v72, s37
	ds_read_b128 v[86:89], v72
	ds_read_b128 v[90:93], v72 offset:16
	ds_read_b128 v[94:97], v72 offset:32
	ds_read_b128 v[98:101], v72 offset:48
	ds_read2_b32 v[162:163], v72 offset0:16 offset1:36
	ds_read_b128 v[102:105], v72 offset:80
	ds_read_b128 v[106:109], v72 offset:96
	ds_read_b128 v[110:113], v72 offset:112
	ds_read_b128 v[114:117], v72 offset:128
	ds_read_b128 v[118:121], v72 offset:160
	ds_read_b128 v[122:125], v72 offset:176
	ds_read_b128 v[126:129], v72 offset:192
	ds_read_b128 v[130:133], v72 offset:208
	ds_read2_b32 v[164:165], v72 offset0:56 offset1:76
	ds_read_b128 v[134:137], v72 offset:240
	ds_read_b128 v[138:141], v72 offset:256
	ds_read_b128 v[142:145], v72 offset:272
	ds_read_b128 v[146:149], v72 offset:288
	s_waitcnt lgkmcnt(14)
	v_mov_b32_e32 v72, v89
	v_mov_b32_e32 v80, v93
	v_mov_b32_e32 v166, v97
	v_mov_b32_e32 v168, v101
	s_waitcnt lgkmcnt(12)
	v_mov_b32_e32 v170, v105
	s_waitcnt lgkmcnt(11)
	v_mov_b32_e32 v172, v109
	s_waitcnt lgkmcnt(10)
	v_mov_b32_e32 v174, v113
	s_waitcnt lgkmcnt(9)
	v_mov_b32_e32 v176, v117
	v_mov_b32_e32 v178, v163
	s_add_u32 s6, s6, 0x48000
	s_waitcnt lgkmcnt(8)
	v_mov_b32_e32 v180, v121
	s_waitcnt lgkmcnt(7)
	v_mov_b32_e32 v182, v125
	s_waitcnt lgkmcnt(6)
	v_mov_b32_e32 v184, v129
	s_waitcnt lgkmcnt(5)
	v_mov_b32_e32 v186, v133
	s_addc_u32 s7, s7, 0
	s_addk_i32 s37, 0x140
	s_waitcnt lgkmcnt(3)
	v_mov_b32_e32 v188, v137
	s_waitcnt lgkmcnt(2)
	v_mov_b32_e32 v190, v141
	s_waitcnt lgkmcnt(1)
	v_mov_b32_e32 v192, v145
	s_waitcnt lgkmcnt(0)
	v_mov_b32_e32 v194, v149
	v_mov_b32_e32 v196, v165
	s_cmp_eq_u32 s6, 0x900000
	s_waitcnt vmcnt(7)
; #define LAS __attribute__((address_space(3)))
; __device__ __forceinline__ void p_adaln_partial(const Frame& F, const float* __restrict__ c, const float* __restrict__ cctx, const float* __restrict__ w_ada, float* modp) {
;     ...
;         for (int kk = 0; kk < 128; ++kk) {
;             const f32x4 w = *(const f32x4*)(wp + (size_t)kk * NMODC);
;             const LAS f32x4* cp = (const LAS f32x4*)(ca + kk * 20); const f32x4 c0 = cp[0], c1 = cp[1], c2 = cp[2], c3 = cp[3]; const float c16 = ca[kk * 20 + 16];
; #pragma unroll
;             for (int j = 0; j < 4; ++j) { acc[j] += c0[j] * w; acc[4 + j] += c1[j] * w; acc[8 + j] += c2[j] * w; acc[12 + j] += c3[j] * w; }
;             acc[16] += c16 * w; }
	v_pk_fma_f32 v[68:69], v[200:201], v[86:87], v[68:69] op_sel_hi:[1,0,1]
	v_pk_fma_f32 v[66:67], v[198:199], v[86:87], v[66:67] op_sel_hi:[1,0,1]
	v_pk_fma_f32 v[64:65], v[200:201], v[86:87], v[64:65] op_sel:[0,1,0]
	v_pk_fma_f32 v[62:63], v[198:199], v[86:87], v[62:63] op_sel:[0,1,0]
	v_pk_fma_f32 v[58:59], v[198:199], v[88:89], v[58:59] op_sel_hi:[1,0,1]
	v_pk_fma_f32 v[60:61], v[200:201], v[88:89], v[60:61] op_sel_hi:[1,0,1]
	v_pk_fma_f32 v[54:55], v[198:199], v[72:73], v[54:55] op_sel_hi:[1,0,1]
	v_pk_fma_f32 v[56:57], v[200:201], v[72:73], v[56:57] op_sel_hi:[1,0,1]
	v_pk_fma_f32 v[52:53], v[200:201], v[90:91], v[52:53] op_sel_hi:[1,0,1]
	v_pk_fma_f32 v[50:51], v[198:199], v[90:91], v[50:51] op_sel_hi:[1,0,1]
	v_pk_fma_f32 v[48:49], v[200:201], v[90:91], v[48:49] op_sel:[0,1,0]
	v_pk_fma_f32 v[46:47], v[198:199], v[90:91], v[46:47] op_sel:[0,1,0]
	v_pk_fma_f32 v[42:43], v[198:199], v[92:93], v[42:43] op_sel_hi:[1,0,1]
	v_pk_fma_f32 v[44:45], v[200:201], v[92:93], v[44:45] op_sel_hi:[1,0,1]
	v_pk_fma_f32 v[38:39], v[198:199], v[80:81], v[38:39] op_sel_hi:[1,0,1]
	v_pk_fma_f32 v[40:41], v[200:201], v[80:81], v[40:41] op_sel_hi:[1,0,1]
	v_pk_fma_f32 v[36:37], v[200:201], v[94:95], v[36:37] op_sel_hi:[1,0,1]
	v_pk_fma_f32 v[34:35], v[198:199], v[94:95], v[34:35] op_sel_hi:[1,0,1]
	v_pk_fma_f32 v[32:33], v[200:201], v[94:95], v[32:33] op_sel:[0,1,0]
	v_pk_fma_f32 v[30:31], v[198:199], v[94:95], v[30:31] op_sel:[0,1,0]
	v_pk_fma_f32 v[26:27], v[198:199], v[96:97], v[26:27] op_sel_hi:[1,0,1]
	v_pk_fma_f32 v[28:29], v[200:201], v[96:97], v[28:29] op_sel_hi:[1,0,1]
	v_pk_fma_f32 v[22:23], v[198:199], v[166:167], v[22:23] op_sel_hi:[1,0,1]
	v_pk_fma_f32 v[24:25], v[200:201], v[166:167], v[24:25] op_sel_hi:[1,0,1]
	v_pk_fma_f32 v[20:21], v[200:201], v[98:99], v[20:21] op_sel_hi:[1,0,1]
	v_pk_fma_f32 v[18:19], v[198:199], v[98:99], v[18:19] op_sel_hi:[1,0,1]
	v_pk_fma_f32 v[16:17], v[200:201], v[98:99], v[16:17] op_sel:[0,1,0]
	v_pk_fma_f32 v[14:15], v[198:199], v[98:99], v[14:15] op_sel:[0,1,0]
	v_pk_fma_f32 v[10:11], v[198:199], v[100:101], v[10:11] op_sel_hi:[1,0,1]
	v_pk_fma_f32 v[12:13], v[200:201], v[100:101], v[12:13] op_sel_hi:[1,0,1]
	v_pk_fma_f32 v[6:7], v[198:199], v[168:169], v[6:7] op_sel_hi:[1,0,1]
	v_pk_fma_f32 v[8:9], v[200:201], v[168:169], v[8:9] op_sel_hi:[1,0,1]
	v_pk_fma_f32 v[2:3], v[198:199], v[162:163], v[2:3] op_sel_hi:[1,0,1]
	v_pk_fma_f32 v[4:5], v[200:201], v[162:163], v[4:5] op_sel_hi:[1,0,1]
	s_waitcnt vmcnt(6)
	v_pk_fma_f32 v[66:67], v[202:203], v[102:103], v[66:67] op_sel_hi:[1,0,1]
	v_pk_fma_f32 v[68:69], v[204:205], v[102:103], v[68:69] op_sel_hi:[1,0,1]
	v_pk_fma_f32 v[62:63], v[202:203], v[102:103], v[62:63] op_sel:[0,1,0]
	v_pk_fma_f32 v[64:65], v[204:205], v[102:103], v[64:65] op_sel:[0,1,0]
	v_pk_fma_f32 v[58:59], v[202:203], v[104:105], v[58:59] op_sel_hi:[1,0,1]
	v_pk_fma_f32 v[60:61], v[204:205], v[104:105], v[60:61] op_sel_hi:[1,0,1]
	v_pk_fma_f32 v[50:51], v[202:203], v[106:107], v[50:51] op_sel_hi:[1,0,1]
	v_pk_fma_f32 v[52:53], v[204:205], v[106:107], v[52:53] op_sel_hi:[1,0,1]
	v_pk_fma_f32 v[46:47], v[202:203], v[106:107], v[46:47] op_sel:[0,1,0]
	v_pk_fma_f32 v[48:49], v[204:205], v[106:107], v[48:49] op_sel:[0,1,0]
	v_pk_fma_f32 v[42:43], v[202:203], v[108:109], v[42:43] op_sel_hi:[1,0,1]
	v_pk_fma_f32 v[44:45], v[204:205], v[108:109], v[44:45] op_sel_hi:[1,0,1]
	v_pk_fma_f32 v[34:35], v[202:203], v[110:111], v[34:35] op_sel_hi:[1,0,1]
	v_pk_fma_f32 v[36:37], v[204:205], v[110:111], v[36:37] op_sel_hi:[1,0,1]
	v_pk_fma_f32 v[30:31], v[202:203], v[110:111], v[30:31] op_sel:[0,1,0]
	v_pk_fma_f32 v[32:33], v[204:205], v[110:111], v[32:33] op_sel:[0,1,0]
	v_pk_fma_f32 v[26:27], v[202:203], v[112:113], v[26:27] op_sel_hi:[1,0,1]
	v_pk_fma_f32 v[28:29], v[204:205], v[112:113], v[28:29] op_sel_hi:[1,0,1]
	v_pk_fma_f32 v[18:19], v[202:203], v[114:115], v[18:19] op_sel_hi:[1,0,1]
	v_pk_fma_f32 v[20:21], v[204:205], v[114:115], v[20:21] op_sel_hi:[1,0,1]
	v_pk_fma_f32 v[14:15], v[202:203], v[114:115], v[14:15] op_sel:[0,1,0]
	v_pk_fma_f32 v[16:17], v[204:205], v[114:115], v[16:17] op_sel:[0,1,0]
	v_pk_fma_f32 v[10:11], v[202:203], v[116:117], v[10:11] op_sel_hi:[1,0,1]
	v_pk_fma_f32 v[12:13], v[204:205], v[116:117], v[12:13] op_sel_hi:[1,0,1]
	v_pk_fma_f32 v[54:55], v[202:203], v[170:171], v[54:55] op_sel_hi:[1,0,1]
	v_pk_fma_f32 v[56:57], v[204:205], v[170:171], v[56:57] op_sel_hi:[1,0,1]
	v_pk_fma_f32 v[38:39], v[202:203], v[172:173], v[38:39] op_sel_hi:[1,0,1]
	v_pk_fma_f32 v[40:41], v[204:205], v[172:173], v[40:41] op_sel_hi:[1,0,1]
	v_pk_fma_f32 v[22:23], v[202:203], v[174:175], v[22:23] op_sel_hi:[1,0,1]
	v_pk_fma_f32 v[24:25], v[204:205], v[174:175], v[24:25] op_sel_hi:[1,0,1]
	v_pk_fma_f32 v[6:7], v[202:203], v[176:177], v[6:7] op_sel_hi:[1,0,1]
	v_pk_fma_f32 v[8:9], v[204:205], v[176:177], v[8:9] op_sel_hi:[1,0,1]
	v_pk_fma_f32 v[2:3], v[202:203], v[178:179], v[2:3] op_sel_hi:[1,0,1]
	v_pk_fma_f32 v[4:5], v[204:205], v[178:179], v[4:5] op_sel_hi:[1,0,1]
	s_waitcnt vmcnt(5)
; #define LAS __attribute__((address_space(3)))
; __device__ __forceinline__ void p_adaln_partial(const Frame& F, const float* __restrict__ c, const float* __restrict__ cctx, const float* __restrict__ w_ada, float* modp) {
;     ...
;         for (int kk = 0; kk < 128; ++kk) {
;             const f32x4 w = *(const f32x4*)(wp + (size_t)kk * NMODC);
;             const LAS f32x4* cp = (const LAS f32x4*)(ca + kk * 20); const f32x4 c0 = cp[0], c1 = cp[1], c2 = cp[2], c3 = cp[3]; const float c16 = ca[kk * 20 + 16];
; #pragma unroll
;             for (int j = 0; j < 4; ++j) { acc[j] += c0[j] * w; acc[4 + j] += c1[j] * w; acc[8 + j] += c2[j] * w; acc[12 + j] += c3[j] * w; }
;             acc[16] += c16 * w; }
	v_pk_fma_f32 v[68:69], v[208:209], v[118:119], v[68:69] op_sel_hi:[1,0,1]
	v_pk_fma_f32 v[66:67], v[206:207], v[118:119], v[66:67] op_sel_hi:[1,0,1]
	v_pk_fma_f32 v[64:65], v[208:209], v[118:119], v[64:65] op_sel:[0,1,0]
	v_pk_fma_f32 v[62:63], v[206:207], v[118:119], v[62:63] op_sel:[0,1,0]
	v_pk_fma_f32 v[60:61], v[208:209], v[120:121], v[60:61] op_sel_hi:[1,0,1]
	v_pk_fma_f32 v[58:59], v[206:207], v[120:121], v[58:59] op_sel_hi:[1,0,1]
	v_pk_fma_f32 v[52:53], v[208:209], v[122:123], v[52:53] op_sel_hi:[1,0,1]
	v_pk_fma_f32 v[50:51], v[206:207], v[122:123], v[50:51] op_sel_hi:[1,0,1]
	v_pk_fma_f32 v[48:49], v[208:209], v[122:123], v[48:49] op_sel:[0,1,0]
	v_pk_fma_f32 v[46:47], v[206:207], v[122:123], v[46:47] op_sel:[0,1,0]
	v_pk_fma_f32 v[44:45], v[208:209], v[124:125], v[44:45] op_sel_hi:[1,0,1]
	v_pk_fma_f32 v[42:43], v[206:207], v[124:125], v[42:43] op_sel_hi:[1,0,1]
	v_pk_fma_f32 v[36:37], v[208:209], v[126:127], v[36:37] op_sel_hi:[1,0,1]
	v_pk_fma_f32 v[34:35], v[206:207], v[126:127], v[34:35] op_sel_hi:[1,0,1]
	v_pk_fma_f32 v[32:33], v[208:209], v[126:127], v[32:33] op_sel:[0,1,0]
	v_pk_fma_f32 v[30:31], v[206:207], v[126:127], v[30:31] op_sel:[0,1,0]
	v_pk_fma_f32 v[28:29], v[208:209], v[128:129], v[28:29] op_sel_hi:[1,0,1]
	v_pk_fma_f32 v[26:27], v[206:207], v[128:129], v[26:27] op_sel_hi:[1,0,1]
	v_pk_fma_f32 v[20:21], v[208:209], v[130:131], v[20:21] op_sel_hi:[1,0,1]
	v_pk_fma_f32 v[18:19], v[206:207], v[130:131], v[18:19] op_sel_hi:[1,0,1]
	v_pk_fma_f32 v[16:17], v[208:209], v[130:131], v[16:17] op_sel:[0,1,0]
	v_pk_fma_f32 v[14:15], v[206:207], v[130:131], v[14:15] op_sel:[0,1,0]
	v_pk_fma_f32 v[12:13], v[208:209], v[132:133], v[12:13] op_sel_hi:[1,0,1]
	v_pk_fma_f32 v[10:11], v[206:207], v[132:133], v[10:11] op_sel_hi:[1,0,1]
	v_pk_fma_f32 v[56:57], v[208:209], v[180:181], v[56:57] op_sel_hi:[1,0,1]
	v_pk_fma_f32 v[54:55], v[206:207], v[180:181], v[54:55] op_sel_hi:[1,0,1]
	v_pk_fma_f32 v[40:41], v[208:209], v[182:183], v[40:41] op_sel_hi:[1,0,1]
	v_pk_fma_f32 v[38:39], v[206:207], v[182:183], v[38:39] op_sel_hi:[1,0,1]
	v_pk_fma_f32 v[24:25], v[208:209], v[184:185], v[24:25] op_sel_hi:[1,0,1]
	v_pk_fma_f32 v[22:23], v[206:207], v[184:185], v[22:23] op_sel_hi:[1,0,1]
	v_pk_fma_f32 v[8:9], v[208:209], v[186:187], v[8:9] op_sel_hi:[1,0,1]
	v_pk_fma_f32 v[6:7], v[206:207], v[186:187], v[6:7] op_sel_hi:[1,0,1]
	v_pk_fma_f32 v[4:5], v[208:209], v[164:165], v[4:5] op_sel_hi:[1,0,1]
	v_pk_fma_f32 v[2:3], v[206:207], v[164:165], v[2:3] op_sel_hi:[1,0,1]
	s_waitcnt vmcnt(4)
	v_pk_fma_f32 v[68:69], v[212:213], v[134:135], v[68:69] op_sel_hi:[1,0,1]
	v_pk_fma_f32 v[66:67], v[210:211], v[134:135], v[66:67] op_sel_hi:[1,0,1]
	v_pk_fma_f32 v[64:65], v[212:213], v[134:135], v[64:65] op_sel:[0,1,0]
	v_pk_fma_f32 v[62:63], v[210:211], v[134:135], v[62:63] op_sel:[0,1,0]
	v_pk_fma_f32 v[60:61], v[212:213], v[136:137], v[60:61] op_sel_hi:[1,0,1]
	v_pk_fma_f32 v[58:59], v[210:211], v[136:137], v[58:59] op_sel_hi:[1,0,1]
	v_pk_fma_f32 v[56:57], v[212:213], v[188:189], v[56:57] op_sel_hi:[1,0,1]
	v_pk_fma_f32 v[54:55], v[210:211], v[188:189], v[54:55] op_sel_hi:[1,0,1]
	v_pk_fma_f32 v[52:53], v[212:213], v[138:139], v[52:53] op_sel_hi:[1,0,1]
	v_pk_fma_f32 v[50:51], v[210:211], v[138:139], v[50:51] op_sel_hi:[1,0,1]
	v_pk_fma_f32 v[48:49], v[212:213], v[138:139], v[48:49] op_sel:[0,1,0]
	v_pk_fma_f32 v[46:47], v[210:211], v[138:139], v[46:47] op_sel:[0,1,0]
	v_pk_fma_f32 v[44:45], v[212:213], v[140:141], v[44:45] op_sel_hi:[1,0,1]
	v_pk_fma_f32 v[42:43], v[210:211], v[140:141], v[42:43] op_sel_hi:[1,0,1]
	v_pk_fma_f32 v[40:41], v[212:213], v[190:191], v[40:41] op_sel_hi:[1,0,1]
	v_pk_fma_f32 v[38:39], v[210:211], v[190:191], v[38:39] op_sel_hi:[1,0,1]
	v_pk_fma_f32 v[36:37], v[212:213], v[142:143], v[36:37] op_sel_hi:[1,0,1]
	v_pk_fma_f32 v[34:35], v[210:211], v[142:143], v[34:35] op_sel_hi:[1,0,1]
	v_pk_fma_f32 v[32:33], v[212:213], v[142:143], v[32:33] op_sel:[0,1,0]
	v_pk_fma_f32 v[30:31], v[210:211], v[142:143], v[30:31] op_sel:[0,1,0]
	v_pk_fma_f32 v[28:29], v[212:213], v[144:145], v[28:29] op_sel_hi:[1,0,1]
	v_pk_fma_f32 v[26:27], v[210:211], v[144:145], v[26:27] op_sel_hi:[1,0,1]
	v_pk_fma_f32 v[24:25], v[212:213], v[192:193], v[24:25] op_sel_hi:[1,0,1]
	v_pk_fma_f32 v[22:23], v[210:211], v[192:193], v[22:23] op_sel_hi:[1,0,1]
	v_pk_fma_f32 v[20:21], v[212:213], v[146:147], v[20:21] op_sel_hi:[1,0,1]
	v_pk_fma_f32 v[18:19], v[210:211], v[146:147], v[18:19] op_sel_hi:[1,0,1]
	v_pk_fma_f32 v[16:17], v[212:213], v[146:147], v[16:17] op_sel:[0,1,0]
	v_pk_fma_f32 v[14:15], v[210:211], v[146:147], v[14:15] op_sel:[0,1,0]
	v_pk_fma_f32 v[12:13], v[212:213], v[148:149], v[12:13] op_sel_hi:[1,0,1]
	v_pk_fma_f32 v[10:11], v[210:211], v[148:149], v[10:11] op_sel_hi:[1,0,1]
	v_pk_fma_f32 v[8:9], v[212:213], v[194:195], v[8:9] op_sel_hi:[1,0,1]
	v_pk_fma_f32 v[6:7], v[210:211], v[194:195], v[6:7] op_sel_hi:[1,0,1]
	v_pk_fma_f32 v[4:5], v[212:213], v[196:197], v[4:5] op_sel_hi:[1,0,1]
	v_pk_fma_f32 v[2:3], v[210:211], v[196:197], v[2:3] op_sel_hi:[1,0,1]
	s_cbranch_scc0 .LBB0_18
; #define LDS_WAIT() asm volatile("s_waitcnt lgkmcnt(0)" ::: "memory")
; __device__ __forceinline__ void p_adaln_partial(const Frame& F, const float* __restrict__ c, const float* __restrict__ cctx, const float* __restrict__ w_ada, float* modp) {
;     ...
;         float* op = modp + ((size_t)(l * 16 + ks) * 17) * NMODC + cb * 256 + F.lane * 4;
; #pragma unroll
;         for (int r = 0; r < 17; ++r) *(f32x4*)(op + (size_t)r * NMODC) = acc[r];
;         LDS_WAIT();
	s_waitcnt vmcnt(0)
	s_lshl_b32 s6, s36, 4
	s_or_b32 s6, s6, s35
	s_mul_i32 s7, s6, 17
	s_mul_i32 s6, s6, 0x132000
	s_mul_hi_i32 s7, s7, 0x12000
	s_add_u32 s6, s17, s6
	s_addc_u32 s7, s18, s7
	s_add_u32 s4, s6, s4
	s_addc_u32 s5, s7, s5
	v_mov_b32_e32 v77, v73
	v_lshl_add_u64 v[78:79], s[4:5], 0, v[76:77]
	global_store_dwordx4 v76, v[66:69], s[4:5]
	s_add_i32 s34, s34, s15
	s_sub_i32 s10, s10, s15
	v_add_co_u32_e32 v66, vcc, s11, v78
	s_cmpk_gt_i32 s34, 0x8ff
	s_nop 0
	v_addc_co_u32_e32 v67, vcc, 0, v79, vcc
	global_store_dwordx4 v[66:67], v[62:65], off
	s_nop 1
	v_add_co_u32_e32 v62, vcc, s20, v78
	s_nop 1
	v_addc_co_u32_e32 v63, vcc, 0, v79, vcc
	global_store_dwordx4 v[62:63], v[58:61], off
	s_nop 1
	v_add_co_u32_e32 v58, vcc, s21, v78
	s_nop 1
	v_addc_co_u32_e32 v59, vcc, 0, v79, vcc
	global_store_dwordx4 v[58:59], v[54:57], off
	s_nop 1
	v_add_co_u32_e32 v54, vcc, s22, v78
	s_nop 1
	v_addc_co_u32_e32 v55, vcc, 0, v79, vcc
	global_store_dwordx4 v[54:55], v[50:53], off
	s_nop 1
	v_add_co_u32_e32 v50, vcc, s23, v78
	s_nop 1
	v_addc_co_u32_e32 v51, vcc, 0, v79, vcc
	global_store_dwordx4 v[50:51], v[46:49], off
	s_nop 1
	v_add_co_u32_e32 v46, vcc, s24, v78
	s_nop 1
	v_addc_co_u32_e32 v47, vcc, 0, v79, vcc
	global_store_dwordx4 v[46:47], v[42:45], off
	s_nop 1
	v_add_co_u32_e32 v42, vcc, s25, v78
	s_nop 1
	v_addc_co_u32_e32 v43, vcc, 0, v79, vcc
	global_store_dwordx4 v[42:43], v[38:41], off
	s_nop 1
	v_add_co_u32_e32 v38, vcc, s26, v78
	s_nop 1
	v_addc_co_u32_e32 v39, vcc, 0, v79, vcc
	global_store_dwordx4 v[38:39], v[34:37], off
	s_nop 1
	v_add_co_u32_e32 v34, vcc, s27, v78
	s_nop 1
	v_addc_co_u32_e32 v35, vcc, 0, v79, vcc
	global_store_dwordx4 v[34:35], v[30:33], off
	s_nop 1
	v_add_co_u32_e32 v30, vcc, s28, v78
	s_nop 1
	v_addc_co_u32_e32 v31, vcc, 0, v79, vcc
	global_store_dwordx4 v[30:31], v[26:29], off
	s_nop 1
	v_add_co_u32_e32 v26, vcc, s29, v78
	s_nop 1
	v_addc_co_u32_e32 v27, vcc, 0, v79, vcc
	global_store_dwordx4 v[26:27], v[22:25], off
	s_nop 1
	v_add_co_u32_e32 v22, vcc, s30, v78
	s_nop 1
	v_addc_co_u32_e32 v23, vcc, 0, v79, vcc
	global_store_dwordx4 v[22:23], v[18:21], off
	s_nop 1
	v_add_co_u32_e32 v18, vcc, s31, v78
	s_nop 1
	v_addc_co_u32_e32 v19, vcc, 0, v79, vcc
	global_store_dwordx4 v[18:19], v[14:17], off
	s_nop 1
	v_add_co_u32_e32 v14, vcc, s33, v78
	s_nop 1
	v_addc_co_u32_e32 v15, vcc, 0, v79, vcc
	global_store_dwordx4 v[14:15], v[10:13], off
	s_nop 1
	v_add_co_u32_e32 v10, vcc, 0x10e000, v78
	s_nop 1
	v_addc_co_u32_e32 v11, vcc, 0, v79, vcc
	global_store_dwordx4 v[10:11], v[6:9], off
	s_nop 1
	v_add_co_u32_e32 v6, vcc, 0x120000, v78
	s_nop 1
	v_addc_co_u32_e32 v7, vcc, 0, v79, vcc
	global_store_dwordx4 v[6:7], v[2:5], off
	s_waitcnt lgkmcnt(0)
	s_cbranch_scc0 .LBB0_15

; __global__ void __launch_bounds__(NTHR, 2) mk_fwd(Args args) {
	.amdhsa_kernel _Z6mk_fwd4Args
		.amdhsa_group_segment_fixed_size 0
		.amdhsa_private_segment_fixed_size 0
		.amdhsa_kernarg_size 488
		.amdhsa_user_sgpr_count 2
		.amdhsa_user_sgpr_dispatch_ptr 0
		.amdhsa_user_sgpr_queue_ptr 0
		.amdhsa_user_sgpr_kernarg_segment_ptr 1
		.amdhsa_user_sgpr_dispatch_id 0
		.amdhsa_user_sgpr_kernarg_preload_length 0
		.amdhsa_user_sgpr_kernarg_preload_offset 0
		.amdhsa_user_sgpr_private_segment_size 0
		.amdhsa_uses_dynamic_stack 0
		.amdhsa_enable_private_segment 0
		.amdhsa_system_sgpr_workgroup_id_x 1
		.amdhsa_system_sgpr_workgroup_id_y 0
		.amdhsa_system_sgpr_workgroup_id_z 0
		.amdhsa_system_sgpr_workgroup_info 0
		.amdhsa_system_vgpr_workitem_id 0
		.amdhsa_next_free_vgpr 255
		.amdhsa_next_free_sgpr 102
		.amdhsa_accum_offset 256
		.amdhsa_reserve_vcc 1
		.amdhsa_float_round_mode_32 0
		.amdhsa_float_round_mode_16_64 0
		.amdhsa_float_denorm_mode_32 3
		.amdhsa_float_denorm_mode_16_64 3
		.amdhsa_dx10_clamp 1
		.amdhsa_ieee_mode 1
		.amdhsa_fp16_overflow 0
		.amdhsa_tg_split 0
		.amdhsa_exception_fp_ieee_invalid_op 0
		.amdhsa_exception_fp_denorm_src 0
		.amdhsa_exception_fp_ieee_div_zero 0
		.amdhsa_exception_fp_ieee_overflow 0
		.amdhsa_exception_fp_ieee_underflow 0
		.amdhsa_exception_fp_ieee_inexact 0
		.amdhsa_exception_int_div_zero 0
	.end_amdhsa_kernel

; __global__ void __launch_bounds__(NTHR, 2) mk_fwd(Args args) {
amdhsa.kernels:
  - .agpr_count:     0
    .args:
      - .offset:         0
        .size:           232
        .value_kind:     by_value
      - .offset:         232
        .size:           4
        .value_kind:     hidden_block_count_x
      - .offset:         236
        .size:           4
        .value_kind:     hidden_block_count_y
      - .offset:         240
        .size:           4
        .value_kind:     hidden_block_count_z
      - .offset:         244
        .size:           2
        .value_kind:     hidden_group_size_x
      - .offset:         246
        .size:           2
        .value_kind:     hidden_group_size_y
      - .offset:         248
        .size:           2
        .value_kind:     hidden_group_size_z
      - .offset:         250
        .size:           2
        .value_kind:     hidden_remainder_x
      - .offset:         252
        .size:           2
        .value_kind:     hidden_remainder_y
      - .offset:         254
        .size:           2
        .value_kind:     hidden_remainder_z
      - .offset:         272
        .size:           8
        .value_kind:     hidden_global_offset_x
      - .offset:         280
        .size:           8
        .value_kind:     hidden_global_offset_y
      - .offset:         288
        .size:           8
        .value_kind:     hidden_global_offset_z
      - .offset:         296
        .size:           2
        .value_kind:     hidden_grid_dims
      - .offset:         352
        .size:           4
        .value_kind:     hidden_dynamic_lds_size
    .group_segment_fixed_size: 0
    .kernarg_segment_align: 8
    .kernarg_segment_size: 488
    .language:       OpenCL C
    .language_version:
      - 2
      - 0
    .max_flat_workgroup_size: 512
    .name:           _Z6mk_fwd4Args
    .private_segment_fixed_size: 0
    .sgpr_count:     108
    .sgpr_spill_count: 96
    .symbol:         _Z6mk_fwd4Args.kd
    .uniform_work_group_size: 1
    .uses_dynamic_stack: false
    .vgpr_count:     255
    .vgpr_spill_count: 0
    .wavefront_size: 64
